# attention: no priority raise over the softmax VALU section
# baseline (speedup 1.0000x reference)
; #define LAS __attribute__((address_space(3)))
; DI unsigned pk2(float lo, float hi) { f32x2 v = {lo, hi}; bf2_t r = __builtin_convertvector(v, bf2_t); return __builtin_bit_cast(unsigned, r); }
; DI void phase_attn(const Params& p, int l, LAS char* lds) {
;     ...
;             __builtin_amdgcn_s_setprio(1);
;             float mx = s0[0];
; #pragma unroll
;             for (int r = 1; r < 16; ++r) mx = fmaxf(mx, s0[r]);
; #pragma unroll
;             for (int r = 0; r < 16; ++r) mx = fmaxf(mx, s1[r]);
;             {
;                 const auto rr = __builtin_amdgcn_permlane32_swap(__float_as_uint(mx), __float_as_uint(mx), false, false);
;                 mx = fmaxf(__uint_as_float(rr[0]), __uint_as_float(rr[1]));
;             }
;             float m_new = m_run;
;             if (__builtin_amdgcn_ballot_w64(mx - m_run > 8.f) != 0ull) {
;                 m_new = fmaxf(m_run, mx);
;                 const float alpha = __builtin_amdgcn_exp2f(m_run - m_new);
;                 m_run = m_new;
;                 l_run *= alpha;
; #pragma unroll
;                 for (int r = 0; r < 16; ++r) { o0[r] *= alpha; o1[r] *= alpha; }
;             }
;             float ps = 0.f;
; #pragma unroll
;             for (int r = 0; r < 16; ++r) { s0[r] = __builtin_amdgcn_exp2f(s0[r] - m_new); s1[r] = __builtin_amdgcn_exp2f(s1[r] - m_new); ps += s0[r] + s1[r]; }
;             l_run += ps;
;             bf16x8 pf[2][2];
; #pragma unroll
;             for (int s2 = 0; s2 < 2; ++s2) {
;                 u32x4 a, c2;
; #pragma unroll
;                 for (int e = 0; e < 4; ++e) { a[e] = pk2(s0[8 * s2 + 2 * e], s0[8 * s2 + 2 * e + 1]); c2[e] = pk2(s1[8 * s2 + 2 * e], s1[8 * s2 + 2 * e + 1]); }
;                 pf[0][s2] = __builtin_bit_cast(bf16x8, a); pf[1][s2] = __builtin_bit_cast(bf16x8, c2);
;             }
;             LAS char* vs = st + 12288;
;             __builtin_amdgcn_s_setprio(0);
.LBB0_290:
	s_or_b64 exec, exec, s[52:53]
	s_nop 4
	v_max_f32_e32 v1, v34, v35
	v_max3_f32 v1, v1, v36, v37
	v_max3_f32 v1, v1, v38, v39
	v_max3_f32 v1, v1, v40, v41
	v_max3_f32 v1, v1, v42, v43
	v_max3_f32 v1, v1, v44, v45
	v_max3_f32 v1, v1, v46, v47
	v_max3_f32 v1, v1, v48, v49
	v_max3_f32 v1, v1, v50, v51
	v_max3_f32 v1, v1, v52, v53
	v_max3_f32 v1, v1, v54, v55
	v_max3_f32 v1, v1, v56, v57
	v_max3_f32 v1, v1, v58, v59
	v_max3_f32 v1, v1, v60, v61
	v_max3_f32 v1, v1, v62, v63
	v_max3_f32 v1, v1, v64, v65
	v_mov_b32_e32 v183, v1
	s_nop 1
	v_permlane32_swap_b32_e32 v1, v183
	v_max_f32_e32 v1, v1, v183
	v_sub_f32_e32 v183, v1, v182
	s_mov_b32 s4, 0x41000000
	v_cmp_lt_f32_e32 vcc, s4, v183
	s_cbranch_vccz .LBB0_292
	v_max_f32_e32 v1, v1, v1
	v_max_f32_e32 v183, v182, v182
	v_max_f32_e32 v1, v183, v1
	v_sub_f32_e32 v182, v182, v1
	v_exp_f32_e32 v182, v182
	s_nop 0
	v_pk_mul_f32 v[32:33], v[32:33], v[182:183] op_sel_hi:[1,0]
	v_pk_mul_f32 v[30:31], v[30:31], v[182:183] op_sel_hi:[1,0]
	v_pk_mul_f32 v[28:29], v[28:29], v[182:183] op_sel_hi:[1,0]
	v_pk_mul_f32 v[26:27], v[26:27], v[182:183] op_sel_hi:[1,0]
	v_pk_mul_f32 v[24:25], v[24:25], v[182:183] op_sel_hi:[1,0]
	v_pk_mul_f32 v[22:23], v[22:23], v[182:183] op_sel_hi:[1,0]
	v_pk_mul_f32 v[20:21], v[20:21], v[182:183] op_sel_hi:[1,0]
	v_pk_mul_f32 v[18:19], v[18:19], v[182:183] op_sel_hi:[1,0]
	v_pk_mul_f32 v[16:17], v[16:17], v[182:183] op_sel_hi:[1,0]
	v_pk_mul_f32 v[14:15], v[14:15], v[182:183] op_sel_hi:[1,0]
	v_pk_mul_f32 v[12:13], v[12:13], v[182:183] op_sel_hi:[1,0]
	v_pk_mul_f32 v[10:11], v[10:11], v[182:183] op_sel_hi:[1,0]
	v_pk_mul_f32 v[8:9], v[8:9], v[182:183] op_sel_hi:[1,0]
	v_pk_mul_f32 v[6:7], v[6:7], v[182:183] op_sel_hi:[1,0]
	v_pk_mul_f32 v[4:5], v[4:5], v[182:183] op_sel_hi:[1,0]
	v_pk_mul_f32 v[2:3], v[2:3], v[182:183] op_sel_hi:[1,0]
	v_mul_f32_e32 v181, v181, v182
	v_mov_b32_e32 v182, v1
.LBB0_292:
	v_sub_f32_e32 v34, v34, v182
	v_sub_f32_e32 v35, v35, v182
	v_sub_f32_e32 v36, v36, v182
	v_sub_f32_e32 v37, v37, v182
	v_sub_f32_e32 v38, v38, v182
	v_sub_f32_e32 v39, v39, v182
	v_sub_f32_e32 v40, v40, v182
	v_sub_f32_e32 v41, v41, v182
	v_sub_f32_e32 v42, v42, v182
	v_sub_f32_e32 v43, v43, v182
	v_sub_f32_e32 v44, v44, v182
	v_sub_f32_e32 v45, v45, v182
	v_sub_f32_e32 v46, v46, v182
	v_sub_f32_e32 v47, v47, v182
	v_sub_f32_e32 v48, v48, v182
	v_sub_f32_e32 v49, v49, v182
	v_sub_f32_e32 v50, v50, v182
	v_sub_f32_e32 v51, v51, v182
	v_sub_f32_e32 v52, v52, v182
	v_sub_f32_e32 v53, v53, v182
	v_sub_f32_e32 v54, v54, v182
	v_sub_f32_e32 v55, v55, v182
	v_sub_f32_e32 v56, v56, v182
	v_sub_f32_e32 v57, v57, v182
	v_sub_f32_e32 v58, v58, v182
	v_sub_f32_e32 v59, v59, v182
	v_sub_f32_e32 v60, v60, v182
	v_sub_f32_e32 v61, v61, v182
	v_sub_f32_e32 v62, v62, v182
	v_sub_f32_e32 v63, v63, v182
	v_sub_f32_e32 v64, v64, v182
	v_sub_f32_e32 v65, v65, v182
	v_exp_f32_e32 v34, v34
	v_exp_f32_e32 v35, v35
	v_exp_f32_e32 v36, v36
	v_exp_f32_e32 v37, v37
	v_exp_f32_e32 v38, v38
	v_exp_f32_e32 v39, v39
	v_exp_f32_e32 v40, v40
	v_exp_f32_e32 v41, v41
	v_exp_f32_e32 v42, v42
	v_exp_f32_e32 v43, v43
	v_exp_f32_e32 v44, v44
	v_exp_f32_e32 v45, v45
	v_exp_f32_e32 v46, v46
	v_exp_f32_e32 v47, v47
	v_exp_f32_e32 v48, v48
	v_exp_f32_e32 v49, v49
	v_exp_f32_e32 v50, v50
	v_exp_f32_e32 v51, v51
	v_exp_f32_e32 v52, v52
	v_exp_f32_e32 v53, v53
	v_exp_f32_e32 v54, v54
	v_exp_f32_e32 v55, v55
	v_exp_f32_e32 v56, v56
	v_exp_f32_e32 v57, v57
	v_exp_f32_e32 v58, v58
	v_exp_f32_e32 v59, v59
	v_exp_f32_e32 v60, v60
	v_exp_f32_e32 v61, v61
	v_exp_f32_e32 v62, v62
	v_exp_f32_e32 v63, v63
	v_exp_f32_e32 v64, v64
	v_exp_f32_e32 v65, v65
	v_add_f32_e32 v184, v34, v35
	v_add_f32_e32 v185, v50, v51
	v_add_f32_e32 v186, v36, v37
	v_add_f32_e32 v187, v52, v53
	v_add_f32_e32 v184, v184, v38
	v_add_f32_e32 v185, v185, v54
	v_add_f32_e32 v186, v186, v39
	v_add_f32_e32 v187, v187, v55
	v_add_f32_e32 v184, v184, v40
	v_add_f32_e32 v185, v185, v56
	v_add_f32_e32 v186, v186, v41
	v_add_f32_e32 v187, v187, v57
	v_add_f32_e32 v184, v184, v42
	v_add_f32_e32 v185, v185, v58
	v_add_f32_e32 v186, v186, v43
	v_add_f32_e32 v187, v187, v59
	v_add_f32_e32 v184, v184, v44
	v_add_f32_e32 v185, v185, v60
	v_add_f32_e32 v186, v186, v45
	v_add_f32_e32 v187, v187, v61
	v_add_f32_e32 v184, v184, v46
	v_add_f32_e32 v185, v185, v62
	v_add_f32_e32 v186, v186, v47
	v_add_f32_e32 v187, v187, v63
	v_add_f32_e32 v184, v184, v48
	v_add_f32_e32 v185, v185, v64
	v_add_f32_e32 v186, v186, v49
	v_add_f32_e32 v187, v187, v65
	v_add_f32_e32 v184, v184, v186
	v_add_f32_e32 v185, v185, v187
	v_add_f32_e32 v1, v184, v185
	v_cvt_pk_bf16_f32 v34, v34, v35
	v_cvt_pk_bf16_f32 v35, v36, v37
	v_cvt_pk_bf16_f32 v36, v38, v39
	v_cvt_pk_bf16_f32 v37, v40, v41
	v_cvt_pk_bf16_f32 v38, v42, v43
	v_cvt_pk_bf16_f32 v39, v44, v45
	v_cvt_pk_bf16_f32 v40, v46, v47
	v_cvt_pk_bf16_f32 v41, v48, v49
	v_cvt_pk_bf16_f32 v42, v50, v51
	v_cvt_pk_bf16_f32 v43, v52, v53
	v_cvt_pk_bf16_f32 v44, v54, v55
	v_cvt_pk_bf16_f32 v45, v56, v57
	v_cvt_pk_bf16_f32 v46, v58, v59
	v_cvt_pk_bf16_f32 v47, v60, v61
	v_cvt_pk_bf16_f32 v48, v62, v63
	v_cvt_pk_bf16_f32 v49, v64, v65
	v_add_f32_e32 v181, v181, v1
	s_cmp_eq_u32 s34, 0
	s_cbranch_scc0 .Lpv_s1
	ds_read_b64 v[50:51], v194 offset:12288
	ds_read_b64 v[54:55], v194 offset:16384
	ds_read_b64 v[52:53], v195 offset:12288
	ds_read_b64 v[56:57], v195 offset:16384
	ds_read_b64 v[58:59], v196 offset:12288
	ds_read_b64 v[62:63], v196 offset:16384
	ds_read_b64 v[60:61], v197 offset:12288
	ds_read_b64 v[64:65], v197 offset:16384
	ds_read_b64 a[0:1], v198 offset:12288
	ds_read_b64 a[4:5], v198 offset:16384
	ds_read_b64 a[2:3], v199 offset:12288
	ds_read_b64 a[6:7], v199 offset:16384
	ds_read_b64 a[8:9], v200 offset:12288
	ds_read_b64 a[12:13], v200 offset:16384
	ds_read_b64 a[10:11], v201 offset:12288
	ds_read_b64 a[14:15], v201 offset:16384
	s_branch .Lpv_rd
